# fused-norm epilogues: the four per-row slot loads issued together (was three serialized round trips)
# baseline (speedup 1.0000x reference)
.LBB0_131:
	s_waitcnt vmcnt(0) lgkmcnt(0)
	s_andn2_b64 vcc, exec, s[54:55]
	s_barrier
	s_cbranch_vccnz .LBB0_133
	v_add_u32_e32 v132, s10, v130
	v_ashrrev_i32_e32 v133, 31, v132
	v_lshl_add_u64 v[132:133], v[132:133], 4, s[2:3]
	global_load_dword v131, v[132:133], off sc1
	global_load_dword v134, v[132:133], off offset:4 sc1
	global_load_dword v244, v[132:133], off offset:8 sc1
	global_load_dword v245, v[132:133], off offset:12 sc1
	v_lshl_add_u32 v130, v130, 2, 0
	s_waitcnt vmcnt(0)
	v_add_f32_e32 v131, 0, v131
	v_add_f32_e32 v131, v131, v134
	v_add_f32_e32 v131, v131, v244
	v_add_f32_e32 v131, v131, v245
	v_fmamk_f32 v131, v131, 0x3a800000, v188
	v_cmp_gt_f32_e32 vcc, s73, v131
	v_mul_f32_e32 v132, 0x4b800000, v131
	s_nop 0
	v_cndmask_b32_e32 v131, v131, v132, vcc
	v_rsq_f32_e32 v131, v131
	s_nop 0
	v_mul_f32_e32 v132, 0x45800000, v131
	v_cndmask_b32_e32 v131, v131, v132, vcc
	ds_write_b32 v130, v131 offset:4096

.LBB0_685:
	s_waitcnt vmcnt(0) lgkmcnt(0)
	s_andn2_b64 vcc, exec, s[2:3]
	s_barrier
	s_cbranch_vccnz .LBB0_687
	v_lshl_or_b32 v2, s48, 6, v0
	v_add_u32_e32 v0, s11, v2
	v_ashrrev_i32_e32 v1, 31, v0
	v_lshl_add_u64 v[0:1], v[0:1], 4, s[84:85]
	global_load_dword v3, v[0:1], off sc1
	global_load_dword v4, v[0:1], off offset:4 sc1
	global_load_dword v244, v[0:1], off offset:8 sc1
	global_load_dword v245, v[0:1], off offset:12 sc1
	s_waitcnt vmcnt(0)
	v_add_f32_e32 v3, 0, v3
	v_add_f32_e32 v3, v3, v4
	v_add_f32_e32 v3, v3, v244
	v_add_f32_e32 v0, v3, v245
	v_fmamk_f32 v0, v0, 0x3a800000, v188
	v_cmp_gt_f32_e32 vcc, s73, v0
	v_mul_f32_e32 v1, 0x4b800000, v0
	s_nop 0
	v_cndmask_b32_e32 v0, v0, v1, vcc
	v_rsq_f32_e32 v0, v0
	s_nop 0
	v_mul_f32_e32 v1, 0x45800000, v0
	v_cndmask_b32_e32 v0, v0, v1, vcc
	v_lshl_add_u32 v1, v2, 2, 0
	ds_write_b32 v1, v0 offset:4096

.LBB0_729:
	s_waitcnt vmcnt(0) lgkmcnt(0)
	s_andn2_b64 vcc, exec, s[2:3]
	s_barrier
	s_cbranch_vccnz .LBB0_731
	v_lshl_or_b32 v132, s48, 6, v130
	v_add_u32_e32 v130, s17, v132
	v_ashrrev_i32_e32 v131, 31, v130
	v_lshl_add_u64 v[130:131], v[130:131], 4, s[84:85]
	global_load_dword v133, v[130:131], off sc1
	global_load_dword v134, v[130:131], off offset:4 sc1
	global_load_dword v244, v[130:131], off offset:8 sc1
	global_load_dword v245, v[130:131], off offset:12 sc1
	s_waitcnt vmcnt(0)
	v_add_f32_e32 v133, 0, v133
	v_add_f32_e32 v133, v133, v134
	v_add_f32_e32 v133, v133, v244
	v_add_f32_e32 v130, v133, v245
	v_fmamk_f32 v130, v130, 0x3a800000, v188
	v_cmp_gt_f32_e32 vcc, s73, v130
	v_mul_f32_e32 v131, 0x4b800000, v130
	s_nop 0
	v_cndmask_b32_e32 v130, v130, v131, vcc
	v_rsq_f32_e32 v130, v130
	s_nop 0
	v_mul_f32_e32 v131, 0x45800000, v130
	v_cndmask_b32_e32 v130, v130, v131, vcc
	v_lshl_add_u32 v131, v132, 2, 0
	ds_write_b32 v131, v130 offset:4096
